# v029 plus the three individually neutral cycle savers together: counted post-loop wait in the P1/P3 epilogues, M0-pad-free LDS-DMA issue, attention hazard pads dropped
# baseline (speedup 1.0000x reference)
.LBB0_127:
	ds_read_b128 v[176:179], v167
	ds_read_b128 v[180:183], v167 offset:1024
	ds_read_b128 v[186:189], v167 offset:2048
	ds_read_b128 v[190:193], v167 offset:3072
	s_add_u32 s40, s38, 0xfff00080
	s_addc_u32 s41, s39, -1
	s_cmp_eq_u32 s54, 60
	s_cselect_b32 s43, s6, s41
	s_cselect_b32 s42, s7, s40
	s_cselect_b32 s41, s9, s29
	s_cselect_b32 s40, s11, s27
	v_lshl_add_u64 v[156:157], s[38:39], 0, v[138:139]
	s_add_i32 m0, s44, 0xc000
	ds_read_b128 v[194:197], v168
	ds_read_b128 v[198:201], v168 offset:1024
	ds_read_b128 v[202:205], v168 offset:2048
	ds_read_b128 v[206:209], v168 offset:3072
	ds_read_b128 v[210:213], v168 offset:4096
	ds_read_b128 v[214:217], v168 offset:5120
	ds_read_b128 v[218:221], v168 offset:6144
	ds_read_b128 v[222:225], v168 offset:7168
	global_load_lds_dwordx4 v[156:157], off
	s_add_i32 m0, s44, 0xe000
	v_lshl_add_u64 v[156:157], s[38:39], 0, v[140:141]
	global_load_lds_dwordx4 v[156:157], off
	s_waitcnt lgkmcnt(8)
	s_barrier
	s_waitcnt lgkmcnt(0)
	v_mfma_f32_16x16x32_bf16 v[124:127], v[176:179], v[194:197], v[124:127]
	v_mfma_f32_16x16x32_bf16 v[124:127], v[180:183], v[198:201], v[124:127]
	v_mfma_f32_16x16x32_bf16 v[120:123], v[186:189], v[194:197], v[120:123]
	v_mfma_f32_16x16x32_bf16 v[120:123], v[190:193], v[198:201], v[120:123]
	v_mfma_f32_16x16x32_bf16 v[108:111], v[176:179], v[202:205], v[108:111]
	v_mfma_f32_16x16x32_bf16 v[108:111], v[180:183], v[206:209], v[108:111]
	v_mfma_f32_16x16x32_bf16 v[104:107], v[186:189], v[202:205], v[104:107]
	v_mfma_f32_16x16x32_bf16 v[104:107], v[190:193], v[206:209], v[104:107]
	v_mfma_f32_16x16x32_bf16 v[92:95], v[176:179], v[210:213], v[92:95]
	v_mfma_f32_16x16x32_bf16 v[92:95], v[180:183], v[214:217], v[92:95]
	v_mfma_f32_16x16x32_bf16 v[88:91], v[186:189], v[210:213], v[88:91]
	v_mfma_f32_16x16x32_bf16 v[88:91], v[190:193], v[214:217], v[88:91]
	v_mfma_f32_16x16x32_bf16 v[76:79], v[176:179], v[218:221], v[76:79]
	v_mfma_f32_16x16x32_bf16 v[76:79], v[180:183], v[222:225], v[76:79]
	v_mfma_f32_16x16x32_bf16 v[72:75], v[186:189], v[218:221], v[72:75]
	v_mfma_f32_16x16x32_bf16 v[72:75], v[190:193], v[222:225], v[72:75]
	s_barrier
	s_add_i32 s55, s72, s5
	v_lshl_add_u64 v[156:157], s[40:41], 0, v[130:131]
	s_mov_b32 m0, s55
	ds_read_b128 v[226:229], v169
	ds_read_b128 v[230:233], v169 offset:1024
	ds_read_b128 v[234:237], v169 offset:2048
	ds_read_b128 v[238:241], v169 offset:3072
	global_load_lds_dwordx4 v[156:157], off
	s_add_i32 m0, s55, 0x2000
	v_lshl_add_u64 v[162:163], s[40:41], 0, v[134:135]
	global_load_lds_dwordx4 v[162:163], off
	s_barrier
	s_waitcnt lgkmcnt(0)
	v_mfma_f32_16x16x32_bf16 v[116:119], v[226:229], v[194:197], v[116:119]
	v_mfma_f32_16x16x32_bf16 v[116:119], v[230:233], v[198:201], v[116:119]
	v_mfma_f32_16x16x32_bf16 v[112:115], v[234:237], v[194:197], v[112:115]
	v_mfma_f32_16x16x32_bf16 v[112:115], v[238:241], v[198:201], v[112:115]
	v_mfma_f32_16x16x32_bf16 v[100:103], v[226:229], v[202:205], v[100:103]
	v_mfma_f32_16x16x32_bf16 v[100:103], v[230:233], v[206:209], v[100:103]
	v_mfma_f32_16x16x32_bf16 v[96:99], v[234:237], v[202:205], v[96:99]
	v_mfma_f32_16x16x32_bf16 v[96:99], v[238:241], v[206:209], v[96:99]
	v_mfma_f32_16x16x32_bf16 v[84:87], v[226:229], v[210:213], v[84:87]
	v_mfma_f32_16x16x32_bf16 v[84:87], v[230:233], v[214:217], v[84:87]
	v_mfma_f32_16x16x32_bf16 v[80:83], v[234:237], v[210:213], v[80:83]
	v_mfma_f32_16x16x32_bf16 v[80:83], v[238:241], v[214:217], v[80:83]
	v_mfma_f32_16x16x32_bf16 v[68:71], v[226:229], v[218:221], v[68:71]
	v_mfma_f32_16x16x32_bf16 v[68:71], v[230:233], v[222:225], v[68:71]
	v_mfma_f32_16x16x32_bf16 v[64:67], v[234:237], v[218:221], v[64:67]
	v_mfma_f32_16x16x32_bf16 v[64:67], v[238:241], v[222:225], v[64:67]
	s_mov_b32 m0, s44
	v_lshl_add_u64 v[170:171], s[42:43], 0, v[128:129]
	s_barrier
	ds_read_b128 v[194:197], v168 offset:16384
	ds_read_b128 v[198:201], v168 offset:17408
	ds_read_b128 v[202:205], v168 offset:18432
	ds_read_b128 v[206:209], v168 offset:19456
	ds_read_b128 v[210:213], v168 offset:20480
	ds_read_b128 v[214:217], v168 offset:21504
	ds_read_b128 v[218:221], v168 offset:22528
	ds_read_b128 v[222:225], v168 offset:23552
	global_load_lds_dwordx4 v[170:171], off
	s_mov_b32 m0, s45
	v_lshl_add_u64 v[242:243], s[42:43], 0, v[132:133]
	global_load_lds_dwordx4 v[242:243], off
	s_barrier
	s_waitcnt lgkmcnt(0)
	v_mfma_f32_16x16x32_bf16 v[60:63], v[176:179], v[194:197], v[60:63]
	v_mfma_f32_16x16x32_bf16 v[60:63], v[180:183], v[198:201], v[60:63]
	v_mfma_f32_16x16x32_bf16 v[56:59], v[186:189], v[194:197], v[56:59]
	v_mfma_f32_16x16x32_bf16 v[56:59], v[190:193], v[198:201], v[56:59]
	v_mfma_f32_16x16x32_bf16 v[44:47], v[176:179], v[202:205], v[44:47]
	v_mfma_f32_16x16x32_bf16 v[44:47], v[180:183], v[206:209], v[44:47]
	v_mfma_f32_16x16x32_bf16 v[40:43], v[186:189], v[202:205], v[40:43]
	v_mfma_f32_16x16x32_bf16 v[40:43], v[190:193], v[206:209], v[40:43]
	v_mfma_f32_16x16x32_bf16 v[28:31], v[176:179], v[210:213], v[28:31]
	v_mfma_f32_16x16x32_bf16 v[28:31], v[180:183], v[214:217], v[28:31]
	v_mfma_f32_16x16x32_bf16 v[24:27], v[186:189], v[210:213], v[24:27]
	v_mfma_f32_16x16x32_bf16 v[24:27], v[190:193], v[214:217], v[24:27]
	v_mfma_f32_16x16x32_bf16 v[12:15], v[176:179], v[218:221], v[12:15]
	v_mfma_f32_16x16x32_bf16 v[12:15], v[180:183], v[222:225], v[12:15]
	v_mfma_f32_16x16x32_bf16 v[8:11], v[186:189], v[218:221], v[8:11]
	v_mfma_f32_16x16x32_bf16 v[8:11], v[190:193], v[222:225], v[8:11]
	s_barrier
	s_add_u32 s62, s40, 0x100000
	s_addc_u32 s63, s41, 0
	s_add_i32 s55, s73, s5
	s_mov_b32 m0, s55
	v_lshl_add_u64 v[176:177], s[62:63], 0, v[130:131]
	global_load_lds_dwordx4 v[176:177], off
	s_add_i32 m0, s55, 0x2000
	v_lshl_add_u64 v[176:177], s[62:63], 0, v[134:135]
	global_load_lds_dwordx4 v[176:177], off
	s_waitcnt vmcnt(6)
	s_barrier
	v_mfma_f32_16x16x32_bf16 v[52:55], v[226:229], v[194:197], v[52:55]
	v_mfma_f32_16x16x32_bf16 v[52:55], v[230:233], v[198:201], v[52:55]
	v_mfma_f32_16x16x32_bf16 v[48:51], v[234:237], v[194:197], v[48:51]
	v_mfma_f32_16x16x32_bf16 v[48:51], v[238:241], v[198:201], v[48:51]
	v_mfma_f32_16x16x32_bf16 v[36:39], v[226:229], v[202:205], v[36:39]
	v_mfma_f32_16x16x32_bf16 v[36:39], v[230:233], v[206:209], v[36:39]
	v_mfma_f32_16x16x32_bf16 v[32:35], v[234:237], v[202:205], v[32:35]
	v_mfma_f32_16x16x32_bf16 v[32:35], v[238:241], v[206:209], v[32:35]
	v_mfma_f32_16x16x32_bf16 v[20:23], v[226:229], v[210:213], v[20:23]
	v_mfma_f32_16x16x32_bf16 v[20:23], v[230:233], v[214:217], v[20:23]
	v_mfma_f32_16x16x32_bf16 v[16:19], v[234:237], v[210:213], v[16:19]
	v_mfma_f32_16x16x32_bf16 v[16:19], v[238:241], v[214:217], v[16:19]
	v_mfma_f32_16x16x32_bf16 v[4:7], v[226:229], v[218:221], v[4:7]
	v_mfma_f32_16x16x32_bf16 v[4:7], v[230:233], v[222:225], v[4:7]
	v_mfma_f32_16x16x32_bf16 v[0:3], v[234:237], v[218:221], v[0:3]
	v_mfma_f32_16x16x32_bf16 v[0:3], v[238:241], v[222:225], v[0:3]
	s_add_i32 s55, 0, 0x18000
	v_add_u32_e32 v137, s55, v165
	s_barrier
	ds_read_b128 v[176:179], v137
	ds_read_b128 v[180:183], v137 offset:1024
	ds_read_b128 v[186:189], v137 offset:2048
	ds_read_b128 v[190:193], v137 offset:3072
	s_add_u32 s42, s42, 0x100000
	s_addc_u32 s43, s43, 0
	s_mov_b32 m0, s46
	v_lshl_add_u64 v[226:227], s[42:43], 0, v[128:129]
	ds_read_b128 v[194:197], v168 offset:32768
	ds_read_b128 v[198:201], v168 offset:33792
	ds_read_b128 v[202:205], v168 offset:34816
	ds_read_b128 v[206:209], v168 offset:35840
	ds_read_b128 v[210:213], v168 offset:36864
	ds_read_b128 v[214:217], v168 offset:37888
	ds_read_b128 v[218:221], v168 offset:38912
	ds_read_b128 v[222:225], v168 offset:39936
	global_load_lds_dwordx4 v[226:227], off
	s_mov_b32 m0, s47
	v_lshl_add_u64 v[226:227], s[42:43], 0, v[132:133]
	global_load_lds_dwordx4 v[226:227], off
	s_waitcnt lgkmcnt(8)
	s_barrier
	s_waitcnt lgkmcnt(0)
	v_mfma_f32_16x16x32_bf16 v[124:127], v[176:179], v[194:197], v[124:127]
	v_mfma_f32_16x16x32_bf16 v[124:127], v[180:183], v[198:201], v[124:127]
	v_mfma_f32_16x16x32_bf16 v[120:123], v[186:189], v[194:197], v[120:123]
	v_mfma_f32_16x16x32_bf16 v[120:123], v[190:193], v[198:201], v[120:123]
	v_mfma_f32_16x16x32_bf16 v[108:111], v[176:179], v[202:205], v[108:111]
	v_mfma_f32_16x16x32_bf16 v[108:111], v[180:183], v[206:209], v[108:111]
	v_mfma_f32_16x16x32_bf16 v[104:107], v[186:189], v[202:205], v[104:107]
	v_mfma_f32_16x16x32_bf16 v[104:107], v[190:193], v[206:209], v[104:107]
	v_mfma_f32_16x16x32_bf16 v[92:95], v[176:179], v[210:213], v[92:95]
	v_mfma_f32_16x16x32_bf16 v[92:95], v[180:183], v[214:217], v[92:95]
	v_mfma_f32_16x16x32_bf16 v[88:91], v[186:189], v[210:213], v[88:91]
	v_mfma_f32_16x16x32_bf16 v[88:91], v[190:193], v[214:217], v[88:91]
	v_mfma_f32_16x16x32_bf16 v[76:79], v[176:179], v[218:221], v[76:79]
	v_mfma_f32_16x16x32_bf16 v[76:79], v[180:183], v[222:225], v[76:79]
	v_mfma_f32_16x16x32_bf16 v[72:75], v[186:189], v[218:221], v[72:75]
	v_mfma_f32_16x16x32_bf16 v[72:75], v[190:193], v[222:225], v[72:75]
	s_barrier
	s_add_i32 s42, 0, 0x1c000
	s_add_i32 s43, s55, s5
	v_add_u32_e32 v137, s42, v165
	v_lshl_add_u64 v[156:157], v[156:157], 0, s[24:25]
	s_mov_b32 m0, s43
	ds_read_b128 v[226:229], v137
	ds_read_b128 v[230:233], v137 offset:1024
	ds_read_b128 v[234:237], v137 offset:2048
	ds_read_b128 v[238:241], v137 offset:3072
	global_load_lds_dwordx4 v[156:157], off
	s_add_i32 m0, s43, 0x2000
	v_lshl_add_u64 v[156:157], v[162:163], 0, s[24:25]
	global_load_lds_dwordx4 v[156:157], off
	s_barrier
	s_waitcnt lgkmcnt(0)
	v_mfma_f32_16x16x32_bf16 v[116:119], v[226:229], v[194:197], v[116:119]
	v_mfma_f32_16x16x32_bf16 v[116:119], v[230:233], v[198:201], v[116:119]
	v_mfma_f32_16x16x32_bf16 v[112:115], v[234:237], v[194:197], v[112:115]
	v_mfma_f32_16x16x32_bf16 v[112:115], v[238:241], v[198:201], v[112:115]
	v_mfma_f32_16x16x32_bf16 v[100:103], v[226:229], v[202:205], v[100:103]
	v_mfma_f32_16x16x32_bf16 v[100:103], v[230:233], v[206:209], v[100:103]
	v_mfma_f32_16x16x32_bf16 v[96:99], v[234:237], v[202:205], v[96:99]
	v_mfma_f32_16x16x32_bf16 v[96:99], v[238:241], v[206:209], v[96:99]
	v_mfma_f32_16x16x32_bf16 v[84:87], v[226:229], v[210:213], v[84:87]
	v_mfma_f32_16x16x32_bf16 v[84:87], v[230:233], v[214:217], v[84:87]
	v_mfma_f32_16x16x32_bf16 v[80:83], v[234:237], v[210:213], v[80:83]
	v_mfma_f32_16x16x32_bf16 v[80:83], v[238:241], v[214:217], v[80:83]
	v_mfma_f32_16x16x32_bf16 v[68:71], v[226:229], v[218:221], v[68:71]
	v_mfma_f32_16x16x32_bf16 v[68:71], v[230:233], v[222:225], v[68:71]
	v_mfma_f32_16x16x32_bf16 v[64:67], v[234:237], v[218:221], v[64:67]
	v_mfma_f32_16x16x32_bf16 v[64:67], v[238:241], v[222:225], v[64:67]
	s_mov_b32 m0, s49
	v_lshl_add_u64 v[156:157], v[170:171], 0, s[24:25]
	s_barrier
	ds_read_b128 v[194:197], v168 offset:49152
	ds_read_b128 v[198:201], v168 offset:50176
	ds_read_b128 v[202:205], v168 offset:51200
	ds_read_b128 v[206:209], v168 offset:52224
	ds_read_b128 v[210:213], v168 offset:53248
	ds_read_b128 v[214:217], v168 offset:54272
	ds_read_b128 v[218:221], v168 offset:55296
	ds_read_b128 v[222:225], v168 offset:56320
	global_load_lds_dwordx4 v[156:157], off
	s_mov_b32 m0, s50
	v_lshl_add_u64 v[156:157], v[242:243], 0, s[24:25]
	global_load_lds_dwordx4 v[156:157], off
	s_barrier
	s_waitcnt lgkmcnt(0)
	v_mfma_f32_16x16x32_bf16 v[60:63], v[176:179], v[194:197], v[60:63]
	v_mfma_f32_16x16x32_bf16 v[60:63], v[180:183], v[198:201], v[60:63]
	v_mfma_f32_16x16x32_bf16 v[56:59], v[186:189], v[194:197], v[56:59]
	v_mfma_f32_16x16x32_bf16 v[56:59], v[190:193], v[198:201], v[56:59]
	v_mfma_f32_16x16x32_bf16 v[44:47], v[176:179], v[202:205], v[44:47]
	v_mfma_f32_16x16x32_bf16 v[44:47], v[180:183], v[206:209], v[44:47]
	v_mfma_f32_16x16x32_bf16 v[40:43], v[186:189], v[202:205], v[40:43]
	v_mfma_f32_16x16x32_bf16 v[40:43], v[190:193], v[206:209], v[40:43]
	v_mfma_f32_16x16x32_bf16 v[28:31], v[176:179], v[210:213], v[28:31]
	v_mfma_f32_16x16x32_bf16 v[28:31], v[180:183], v[214:217], v[28:31]
	v_mfma_f32_16x16x32_bf16 v[24:27], v[186:189], v[210:213], v[24:27]
	v_mfma_f32_16x16x32_bf16 v[24:27], v[190:193], v[214:217], v[24:27]
	v_mfma_f32_16x16x32_bf16 v[12:15], v[176:179], v[218:221], v[12:15]
	v_mfma_f32_16x16x32_bf16 v[12:15], v[180:183], v[222:225], v[12:15]
	v_mfma_f32_16x16x32_bf16 v[8:11], v[186:189], v[218:221], v[8:11]
	v_mfma_f32_16x16x32_bf16 v[8:11], v[190:193], v[222:225], v[8:11]
	s_barrier
	s_add_u32 s40, s40, 0x100080
	s_addc_u32 s41, s41, 0
	s_add_i32 s42, s42, s5
	s_mov_b32 m0, s42
	v_lshl_add_u64 v[156:157], s[40:41], 0, v[130:131]
	global_load_lds_dwordx4 v[156:157], off
	s_add_i32 m0, s42, 0x2000
	v_lshl_add_u64 v[156:157], s[40:41], 0, v[134:135]
	global_load_lds_dwordx4 v[156:157], off
	s_waitcnt vmcnt(6)
	s_barrier
	v_mfma_f32_16x16x32_bf16 v[52:55], v[226:229], v[194:197], v[52:55]
	v_mfma_f32_16x16x32_bf16 v[52:55], v[230:233], v[198:201], v[52:55]
	v_mfma_f32_16x16x32_bf16 v[48:51], v[234:237], v[194:197], v[48:51]
	v_mfma_f32_16x16x32_bf16 v[48:51], v[238:241], v[198:201], v[48:51]
	v_mfma_f32_16x16x32_bf16 v[36:39], v[226:229], v[202:205], v[36:39]
	v_mfma_f32_16x16x32_bf16 v[36:39], v[230:233], v[206:209], v[36:39]
	v_mfma_f32_16x16x32_bf16 v[32:35], v[234:237], v[202:205], v[32:35]
	v_mfma_f32_16x16x32_bf16 v[32:35], v[238:241], v[206:209], v[32:35]
	v_mfma_f32_16x16x32_bf16 v[20:23], v[226:229], v[210:213], v[20:23]
	v_mfma_f32_16x16x32_bf16 v[20:23], v[230:233], v[214:217], v[20:23]
	v_mfma_f32_16x16x32_bf16 v[16:19], v[234:237], v[210:213], v[16:19]
	v_mfma_f32_16x16x32_bf16 v[16:19], v[238:241], v[214:217], v[16:19]
	v_mfma_f32_16x16x32_bf16 v[4:7], v[226:229], v[218:221], v[4:7]
	v_mfma_f32_16x16x32_bf16 v[4:7], v[230:233], v[222:225], v[4:7]
	v_mfma_f32_16x16x32_bf16 v[0:3], v[234:237], v[218:221], v[0:3]
	v_mfma_f32_16x16x32_bf16 v[0:3], v[238:241], v[222:225], v[0:3]
	s_add_i32 s54, s54, 2
	s_add_u32 s38, s38, 0x100
	s_addc_u32 s39, s39, 0
	s_add_u32 s27, s27, 0x100
	s_addc_u32 s29, s29, 0
	s_cmp_gt_u32 s54, 61
	s_barrier
	s_cbranch_scc0 .LBB0_127
	v_lshl_or_b32 v156, s8, 8, v166
	s_waitcnt vmcnt(6)
	v_pk_mul_f32 v[126:127], v[160:161], v[126:127] op_sel_hi:[0,1]
	v_pk_mul_f32 v[124:125], v[160:161], v[124:125] op_sel_hi:[0,1]
	v_pk_mul_f32 v[122:123], v[160:161], v[122:123] op_sel_hi:[0,1]
	v_pk_mul_f32 v[162:163], v[160:161], v[120:121] op_sel_hi:[0,1]
	v_cmp_lt_i32_e64 s[8:9], s74, v156
	s_and_saveexec_b64 s[38:39], s[8:9]
	s_cbranch_execz .LBB0_130
	v_mul_f32_e32 v147, 0xbfb8aa3b, v126
	v_mul_f32_e32 v121, 0xbfb8aa3b, v162
	v_exp_f32_e32 v147, v147
	v_mul_f32_e32 v149, 0xbfb8aa3b, v122
	v_mul_f32_e32 v137, 0xbfb8aa3b, v125
	v_exp_f32_e32 v121, v121
	v_exp_f32_e32 v149, v149
	v_exp_f32_e32 v137, v137
	v_add_f32_e32 v147, 1.0, v147
	v_add_f32_e32 v121, 1.0, v121
	v_rcp_f32_e32 v176, v147
	v_add_f32_e32 v147, 1.0, v149
	v_mul_f32_e32 v149, 0xbfb8aa3b, v127
	v_mul_f32_e32 v120, 0xbfb8aa3b, v124
	v_rcp_f32_e32 v170, v121
	v_add_f32_e32 v121, 1.0, v137
	v_mul_f32_e32 v137, 0xbfb8aa3b, v163
	v_exp_f32_e32 v149, v149
	v_mul_f32_e32 v151, 0xbfb8aa3b, v123
	v_exp_f32_e32 v120, v120
	v_exp_f32_e32 v137, v137
	v_exp_f32_e32 v151, v151
	v_rcp_f32_e32 v178, v147
	v_add_f32_e32 v147, 1.0, v149
	v_add_f32_e32 v120, 1.0, v120
	v_add_f32_e32 v137, 1.0, v137
	v_rcp_f32_e32 v177, v147
	v_add_f32_e32 v147, 1.0, v151
	v_rcp_f32_e32 v120, v120
	v_rcp_f32_e32 v121, v121
	v_rcp_f32_e32 v179, v147
	v_rcp_f32_e32 v171, v137
	v_pk_mul_f32 v[126:127], v[126:127], v[176:177]
	v_pk_mul_f32 v[124:125], v[124:125], v[120:121]
	v_pk_mul_f32 v[122:123], v[122:123], v[178:179]
	v_pk_mul_f32 v[162:163], v[162:163], v[170:171]

.LBB0_301:
	ds_read_b128 v[160:163], v151
	ds_read_b128 v[164:167], v151 offset:1024
	ds_read_b128 v[168:171], v151 offset:2048
	ds_read_b128 v[176:179], v151 offset:3072
	s_add_u32 s44, s42, 0x100
	s_addc_u32 s45, s43, 0
	s_cmp_eq_u32 s83, 12
	s_cselect_b32 s49, s39, s45
	s_cselect_b32 s48, s38, s44
	s_cselect_b32 s47, s37, s82
	s_cselect_b32 s46, s62, s63
	v_lshl_add_u64 v[214:215], s[42:43], 0, v[142:143]
	s_add_i32 m0, s50, 0xc000
	ds_read_b128 v[180:183], v153
	ds_read_b128 v[186:189], v153 offset:1024
	ds_read_b128 v[190:193], v153 offset:2048
	ds_read_b128 v[194:197], v153 offset:3072
	ds_read_b128 v[198:201], v153 offset:4096
	ds_read_b128 v[202:205], v153 offset:5120
	ds_read_b128 v[206:209], v153 offset:6144
	ds_read_b128 v[210:213], v153 offset:7168
	global_load_lds_dwordx4 v[214:215], off
	s_add_i32 m0, s50, 0xe000
	v_lshl_add_u64 v[214:215], s[42:43], 0, v[144:145]
	global_load_lds_dwordx4 v[214:215], off
	s_waitcnt lgkmcnt(8)
	s_barrier
	s_waitcnt lgkmcnt(0)
	v_mfma_f32_16x16x32_bf16 v[124:127], v[160:163], v[180:183], v[124:127]
	v_mfma_f32_16x16x32_bf16 v[124:127], v[164:167], v[186:189], v[124:127]
	v_mfma_f32_16x16x32_bf16 v[120:123], v[168:171], v[180:183], v[120:123]
	v_mfma_f32_16x16x32_bf16 v[120:123], v[176:179], v[186:189], v[120:123]
	v_mfma_f32_16x16x32_bf16 v[112:115], v[160:163], v[190:193], v[112:115]
	v_mfma_f32_16x16x32_bf16 v[112:115], v[164:167], v[194:197], v[112:115]
	v_mfma_f32_16x16x32_bf16 v[104:107], v[168:171], v[190:193], v[104:107]
	v_mfma_f32_16x16x32_bf16 v[104:107], v[176:179], v[194:197], v[104:107]
	v_mfma_f32_16x16x32_bf16 v[96:99], v[160:163], v[198:201], v[96:99]
	v_mfma_f32_16x16x32_bf16 v[96:99], v[164:167], v[202:205], v[96:99]
	v_mfma_f32_16x16x32_bf16 v[88:91], v[168:171], v[198:201], v[88:91]
	v_mfma_f32_16x16x32_bf16 v[88:91], v[176:179], v[202:205], v[88:91]
	v_mfma_f32_16x16x32_bf16 v[80:83], v[160:163], v[206:209], v[80:83]
	v_mfma_f32_16x16x32_bf16 v[80:83], v[164:167], v[210:213], v[80:83]
	v_mfma_f32_16x16x32_bf16 v[72:75], v[168:171], v[206:209], v[72:75]
	v_mfma_f32_16x16x32_bf16 v[72:75], v[176:179], v[210:213], v[72:75]
	s_barrier
	s_add_i32 s42, s76, s5
	v_lshl_add_u64 v[230:231], s[46:47], 0, v[132:133]
	s_mov_b32 m0, s42
	ds_read_b128 v[214:217], v155
	ds_read_b128 v[218:221], v155 offset:1024
	ds_read_b128 v[222:225], v155 offset:2048
	ds_read_b128 v[226:229], v155 offset:3072
	global_load_lds_dwordx4 v[230:231], off
	s_add_i32 m0, s42, 0x2000
	v_lshl_add_u64 v[232:233], s[46:47], 0, v[128:129]
	global_load_lds_dwordx4 v[232:233], off
	s_barrier
	s_waitcnt lgkmcnt(0)
	v_mfma_f32_16x16x32_bf16 v[116:119], v[214:217], v[180:183], v[116:119]
	v_mfma_f32_16x16x32_bf16 v[116:119], v[218:221], v[186:189], v[116:119]
	v_mfma_f32_16x16x32_bf16 v[108:111], v[222:225], v[180:183], v[108:111]
	v_mfma_f32_16x16x32_bf16 v[108:111], v[226:229], v[186:189], v[108:111]
	v_mfma_f32_16x16x32_bf16 v[100:103], v[214:217], v[190:193], v[100:103]
	v_mfma_f32_16x16x32_bf16 v[100:103], v[218:221], v[194:197], v[100:103]
	v_mfma_f32_16x16x32_bf16 v[92:95], v[222:225], v[190:193], v[92:95]
	v_mfma_f32_16x16x32_bf16 v[92:95], v[226:229], v[194:197], v[92:95]
	v_mfma_f32_16x16x32_bf16 v[84:87], v[214:217], v[198:201], v[84:87]
	v_mfma_f32_16x16x32_bf16 v[84:87], v[218:221], v[202:205], v[84:87]
	v_mfma_f32_16x16x32_bf16 v[76:79], v[222:225], v[198:201], v[76:79]
	v_mfma_f32_16x16x32_bf16 v[76:79], v[226:229], v[202:205], v[76:79]
	v_mfma_f32_16x16x32_bf16 v[68:71], v[214:217], v[206:209], v[68:71]
	v_mfma_f32_16x16x32_bf16 v[68:71], v[218:221], v[210:213], v[68:71]
	v_mfma_f32_16x16x32_bf16 v[64:67], v[222:225], v[206:209], v[64:67]
	v_mfma_f32_16x16x32_bf16 v[64:67], v[226:229], v[210:213], v[64:67]
	s_mov_b32 m0, s50
	v_lshl_add_u64 v[234:235], s[48:49], 0, v[134:135]
	s_barrier
	ds_read_b128 v[180:183], v153 offset:16384
	ds_read_b128 v[186:189], v153 offset:17408
	ds_read_b128 v[190:193], v153 offset:18432
	ds_read_b128 v[194:197], v153 offset:19456
	ds_read_b128 v[198:201], v153 offset:20480
	ds_read_b128 v[202:205], v153 offset:21504
	ds_read_b128 v[206:209], v153 offset:22528
	ds_read_b128 v[210:213], v153 offset:23552
	global_load_lds_dwordx4 v[234:235], off
	s_mov_b32 m0, s51
	v_lshl_add_u64 v[236:237], s[48:49], 0, v[130:131]
	global_load_lds_dwordx4 v[236:237], off
	s_barrier
	s_waitcnt lgkmcnt(0)
	v_mfma_f32_16x16x32_bf16 v[60:63], v[160:163], v[180:183], v[60:63]
	v_mfma_f32_16x16x32_bf16 v[60:63], v[164:167], v[186:189], v[60:63]
	v_mfma_f32_16x16x32_bf16 v[56:59], v[168:171], v[180:183], v[56:59]
	v_mfma_f32_16x16x32_bf16 v[56:59], v[176:179], v[186:189], v[56:59]
	v_mfma_f32_16x16x32_bf16 v[48:51], v[160:163], v[190:193], v[48:51]
	v_mfma_f32_16x16x32_bf16 v[48:51], v[164:167], v[194:197], v[48:51]
	v_mfma_f32_16x16x32_bf16 v[40:43], v[168:171], v[190:193], v[40:43]
	v_mfma_f32_16x16x32_bf16 v[40:43], v[176:179], v[194:197], v[40:43]
	v_mfma_f32_16x16x32_bf16 v[32:35], v[160:163], v[198:201], v[32:35]
	v_mfma_f32_16x16x32_bf16 v[32:35], v[164:167], v[202:205], v[32:35]
	v_mfma_f32_16x16x32_bf16 v[24:27], v[168:171], v[198:201], v[24:27]
	v_mfma_f32_16x16x32_bf16 v[24:27], v[176:179], v[202:205], v[24:27]
	v_mfma_f32_16x16x32_bf16 v[16:19], v[160:163], v[206:209], v[16:19]
	v_mfma_f32_16x16x32_bf16 v[16:19], v[164:167], v[210:213], v[16:19]
	v_mfma_f32_16x16x32_bf16 v[8:11], v[168:171], v[206:209], v[8:11]
	v_mfma_f32_16x16x32_bf16 v[8:11], v[176:179], v[210:213], v[8:11]
	s_barrier
	s_add_u32 s42, s46, 0x40000
	s_addc_u32 s43, s47, 0
	s_add_i32 s84, s77, s5
	s_mov_b32 m0, s84
	v_lshl_add_u64 v[160:161], s[42:43], 0, v[132:133]
	global_load_lds_dwordx4 v[160:161], off
	s_add_i32 m0, s84, 0x2000
	v_lshl_add_u64 v[160:161], s[42:43], 0, v[128:129]
	global_load_lds_dwordx4 v[160:161], off
	s_waitcnt vmcnt(6)
	s_barrier
	v_mfma_f32_16x16x32_bf16 v[52:55], v[214:217], v[180:183], v[52:55]
	v_mfma_f32_16x16x32_bf16 v[52:55], v[218:221], v[186:189], v[52:55]
	v_mfma_f32_16x16x32_bf16 v[44:47], v[222:225], v[180:183], v[44:47]
	v_mfma_f32_16x16x32_bf16 v[44:47], v[226:229], v[186:189], v[44:47]
	v_mfma_f32_16x16x32_bf16 v[36:39], v[214:217], v[190:193], v[36:39]
	v_mfma_f32_16x16x32_bf16 v[36:39], v[218:221], v[194:197], v[36:39]
	v_mfma_f32_16x16x32_bf16 v[28:31], v[222:225], v[190:193], v[28:31]
	v_mfma_f32_16x16x32_bf16 v[28:31], v[226:229], v[194:197], v[28:31]
	v_mfma_f32_16x16x32_bf16 v[20:23], v[214:217], v[198:201], v[20:23]
	v_mfma_f32_16x16x32_bf16 v[20:23], v[218:221], v[202:205], v[20:23]
	v_mfma_f32_16x16x32_bf16 v[12:15], v[222:225], v[198:201], v[12:15]
	v_mfma_f32_16x16x32_bf16 v[12:15], v[226:229], v[202:205], v[12:15]
	v_mfma_f32_16x16x32_bf16 v[4:7], v[214:217], v[206:209], v[4:7]
	v_mfma_f32_16x16x32_bf16 v[4:7], v[218:221], v[210:213], v[4:7]
	v_mfma_f32_16x16x32_bf16 v[0:3], v[222:225], v[206:209], v[0:3]
	v_mfma_f32_16x16x32_bf16 v[0:3], v[226:229], v[210:213], v[0:3]
	s_add_i32 s84, 0, 0x18000
	v_add_u32_e32 v157, s84, v139
	s_barrier
	ds_read_b128 v[160:163], v157
	ds_read_b128 v[164:167], v157 offset:1024
	ds_read_b128 v[168:171], v157 offset:2048
	ds_read_b128 v[176:179], v157 offset:3072
	s_add_u32 s42, s48, 0x170000
	s_addc_u32 s43, s49, 0
	s_mov_b32 m0, s52
	v_lshl_add_u64 v[214:215], s[42:43], 0, v[134:135]
	ds_read_b128 v[180:183], v153 offset:32768
	ds_read_b128 v[186:189], v153 offset:33792
	ds_read_b128 v[190:193], v153 offset:34816
	ds_read_b128 v[194:197], v153 offset:35840
	ds_read_b128 v[198:201], v153 offset:36864
	ds_read_b128 v[202:205], v153 offset:37888
	ds_read_b128 v[206:209], v153 offset:38912
	ds_read_b128 v[210:213], v153 offset:39936
	global_load_lds_dwordx4 v[214:215], off
	s_mov_b32 m0, s53
	v_lshl_add_u64 v[214:215], s[42:43], 0, v[130:131]
	global_load_lds_dwordx4 v[214:215], off
	s_waitcnt lgkmcnt(8)
	s_barrier
	s_waitcnt lgkmcnt(0)
	v_mfma_f32_16x16x32_bf16 v[124:127], v[160:163], v[180:183], v[124:127]
	v_mfma_f32_16x16x32_bf16 v[124:127], v[164:167], v[186:189], v[124:127]
	v_mfma_f32_16x16x32_bf16 v[120:123], v[168:171], v[180:183], v[120:123]
	v_mfma_f32_16x16x32_bf16 v[120:123], v[176:179], v[186:189], v[120:123]
	v_mfma_f32_16x16x32_bf16 v[112:115], v[160:163], v[190:193], v[112:115]
	v_mfma_f32_16x16x32_bf16 v[112:115], v[164:167], v[194:197], v[112:115]
	v_mfma_f32_16x16x32_bf16 v[104:107], v[168:171], v[190:193], v[104:107]
	v_mfma_f32_16x16x32_bf16 v[104:107], v[176:179], v[194:197], v[104:107]
	v_mfma_f32_16x16x32_bf16 v[96:99], v[160:163], v[198:201], v[96:99]
	v_mfma_f32_16x16x32_bf16 v[96:99], v[164:167], v[202:205], v[96:99]
	v_mfma_f32_16x16x32_bf16 v[88:91], v[168:171], v[198:201], v[88:91]
	v_mfma_f32_16x16x32_bf16 v[88:91], v[176:179], v[202:205], v[88:91]
	v_mfma_f32_16x16x32_bf16 v[80:83], v[160:163], v[206:209], v[80:83]
	v_mfma_f32_16x16x32_bf16 v[80:83], v[164:167], v[210:213], v[80:83]
	v_mfma_f32_16x16x32_bf16 v[72:75], v[168:171], v[206:209], v[72:75]
	v_mfma_f32_16x16x32_bf16 v[72:75], v[176:179], v[210:213], v[72:75]
	s_barrier
	s_add_i32 s48, 0, 0x1c000
	s_add_i32 s42, s84, s5
	v_add_u32_e32 v157, s48, v139
	v_lshl_add_u64 v[230:231], v[230:231], 0, s[10:11]
	s_mov_b32 m0, s42
	ds_read_b128 v[214:217], v157
	ds_read_b128 v[218:221], v157 offset:1024
	ds_read_b128 v[222:225], v157 offset:2048
	ds_read_b128 v[226:229], v157 offset:3072
	global_load_lds_dwordx4 v[230:231], off
	s_add_i32 m0, s42, 0x2000
	v_lshl_add_u64 v[230:231], v[232:233], 0, s[10:11]
	global_load_lds_dwordx4 v[230:231], off
	s_barrier
	s_waitcnt lgkmcnt(0)
	v_mfma_f32_16x16x32_bf16 v[116:119], v[214:217], v[180:183], v[116:119]
	v_mfma_f32_16x16x32_bf16 v[116:119], v[218:221], v[186:189], v[116:119]
	v_mfma_f32_16x16x32_bf16 v[108:111], v[222:225], v[180:183], v[108:111]
	v_mfma_f32_16x16x32_bf16 v[108:111], v[226:229], v[186:189], v[108:111]
	v_mfma_f32_16x16x32_bf16 v[100:103], v[214:217], v[190:193], v[100:103]
	v_mfma_f32_16x16x32_bf16 v[100:103], v[218:221], v[194:197], v[100:103]
	v_mfma_f32_16x16x32_bf16 v[92:95], v[222:225], v[190:193], v[92:95]
	v_mfma_f32_16x16x32_bf16 v[92:95], v[226:229], v[194:197], v[92:95]
	v_mfma_f32_16x16x32_bf16 v[84:87], v[214:217], v[198:201], v[84:87]
	v_mfma_f32_16x16x32_bf16 v[84:87], v[218:221], v[202:205], v[84:87]
	v_mfma_f32_16x16x32_bf16 v[76:79], v[222:225], v[198:201], v[76:79]
	v_mfma_f32_16x16x32_bf16 v[76:79], v[226:229], v[202:205], v[76:79]
	v_mfma_f32_16x16x32_bf16 v[68:71], v[214:217], v[206:209], v[68:71]
	v_mfma_f32_16x16x32_bf16 v[68:71], v[218:221], v[210:213], v[68:71]
	v_mfma_f32_16x16x32_bf16 v[64:67], v[222:225], v[206:209], v[64:67]
	v_mfma_f32_16x16x32_bf16 v[64:67], v[226:229], v[210:213], v[64:67]
	s_mov_b32 m0, s55
	v_lshl_add_u64 v[230:231], v[234:235], 0, s[10:11]
	s_barrier
	ds_read_b128 v[180:183], v153 offset:49152
	ds_read_b128 v[186:189], v153 offset:50176
	ds_read_b128 v[190:193], v153 offset:51200
	ds_read_b128 v[194:197], v153 offset:52224
	ds_read_b128 v[198:201], v153 offset:53248
	ds_read_b128 v[202:205], v153 offset:54272
	ds_read_b128 v[206:209], v153 offset:55296
	ds_read_b128 v[210:213], v153 offset:56320
	global_load_lds_dwordx4 v[230:231], off
	s_mov_b32 m0, s61
	v_lshl_add_u64 v[230:231], v[236:237], 0, s[10:11]
	global_load_lds_dwordx4 v[230:231], off
	s_barrier
	s_waitcnt lgkmcnt(0)
	v_mfma_f32_16x16x32_bf16 v[60:63], v[160:163], v[180:183], v[60:63]
	v_mfma_f32_16x16x32_bf16 v[60:63], v[164:167], v[186:189], v[60:63]
	v_mfma_f32_16x16x32_bf16 v[56:59], v[168:171], v[180:183], v[56:59]
	v_mfma_f32_16x16x32_bf16 v[56:59], v[176:179], v[186:189], v[56:59]
	v_mfma_f32_16x16x32_bf16 v[48:51], v[160:163], v[190:193], v[48:51]
	v_mfma_f32_16x16x32_bf16 v[48:51], v[164:167], v[194:197], v[48:51]
	v_mfma_f32_16x16x32_bf16 v[40:43], v[168:171], v[190:193], v[40:43]
	v_mfma_f32_16x16x32_bf16 v[40:43], v[176:179], v[194:197], v[40:43]
	v_mfma_f32_16x16x32_bf16 v[32:35], v[160:163], v[198:201], v[32:35]
	v_mfma_f32_16x16x32_bf16 v[32:35], v[164:167], v[202:205], v[32:35]
	v_mfma_f32_16x16x32_bf16 v[24:27], v[168:171], v[198:201], v[24:27]
	v_mfma_f32_16x16x32_bf16 v[24:27], v[176:179], v[202:205], v[24:27]
	v_mfma_f32_16x16x32_bf16 v[16:19], v[160:163], v[206:209], v[16:19]
	v_mfma_f32_16x16x32_bf16 v[16:19], v[164:167], v[210:213], v[16:19]
	v_mfma_f32_16x16x32_bf16 v[8:11], v[168:171], v[206:209], v[8:11]
	v_mfma_f32_16x16x32_bf16 v[8:11], v[176:179], v[210:213], v[8:11]
	s_barrier
	s_add_u32 s42, s46, 0x40080
	s_addc_u32 s43, s47, 0
	s_add_i32 s46, s48, s5
	s_mov_b32 m0, s46
	v_lshl_add_u64 v[160:161], s[42:43], 0, v[132:133]
	global_load_lds_dwordx4 v[160:161], off
	s_add_i32 m0, s46, 0x2000
	v_lshl_add_u64 v[160:161], s[42:43], 0, v[128:129]
	global_load_lds_dwordx4 v[160:161], off
	s_waitcnt vmcnt(6)
	s_barrier
	v_mfma_f32_16x16x32_bf16 v[52:55], v[214:217], v[180:183], v[52:55]
	v_mfma_f32_16x16x32_bf16 v[52:55], v[218:221], v[186:189], v[52:55]
	v_mfma_f32_16x16x32_bf16 v[44:47], v[222:225], v[180:183], v[44:47]
	v_mfma_f32_16x16x32_bf16 v[44:47], v[226:229], v[186:189], v[44:47]
	v_mfma_f32_16x16x32_bf16 v[36:39], v[214:217], v[190:193], v[36:39]
	v_mfma_f32_16x16x32_bf16 v[36:39], v[218:221], v[194:197], v[36:39]
	v_mfma_f32_16x16x32_bf16 v[28:31], v[222:225], v[190:193], v[28:31]
	v_mfma_f32_16x16x32_bf16 v[28:31], v[226:229], v[194:197], v[28:31]
	v_mfma_f32_16x16x32_bf16 v[20:23], v[214:217], v[198:201], v[20:23]
	v_mfma_f32_16x16x32_bf16 v[20:23], v[218:221], v[202:205], v[20:23]
	v_mfma_f32_16x16x32_bf16 v[12:15], v[222:225], v[198:201], v[12:15]
	v_mfma_f32_16x16x32_bf16 v[12:15], v[226:229], v[202:205], v[12:15]
	v_mfma_f32_16x16x32_bf16 v[4:7], v[214:217], v[206:209], v[4:7]
	v_mfma_f32_16x16x32_bf16 v[4:7], v[218:221], v[210:213], v[4:7]
	v_mfma_f32_16x16x32_bf16 v[0:3], v[222:225], v[206:209], v[0:3]
	v_mfma_f32_16x16x32_bf16 v[0:3], v[226:229], v[210:213], v[0:3]
	s_add_i32 s83, s83, 2
	s_add_u32 s63, s63, 0x100
	s_addc_u32 s82, s82, 0
	s_cmp_gt_u32 s83, 13
	s_mov_b64 s[42:43], s[44:45]
	s_barrier
	s_cbranch_scc0 .LBB0_301
	v_lshl_or_b32 v162, s81, 8, v141
	v_lshl_add_u32 v157, s80, 8, v137
	v_ashrrev_i32_e32 v163, 31, v162
	v_mov_b64_e32 v[160:161], s[12:13]
	v_mad_i64_i32 v[164:165], s[42:43], v157, s78, v[160:161]
	v_lshlrev_b64 v[162:163], 1, v[162:163]
	v_lshl_add_u64 v[164:165], v[164:165], 0, v[162:163]
	s_waitcnt vmcnt(6)
	v_pk_mul_f32 v[126:127], v[158:159], v[126:127] op_sel_hi:[0,1]
	v_pk_mul_f32 v[124:125], v[158:159], v[124:125] op_sel_hi:[0,1]
	v_pk_mul_f32 v[166:167], v[158:159], v[122:123] op_sel_hi:[0,1]
	v_pk_mul_f32 v[122:123], v[158:159], v[120:121] op_sel_hi:[0,1]
	v_cvt_pk_bf16_f32 v120, v124, v125
	v_cvt_pk_bf16_f32 v121, v126, v127
	v_cvt_pk_bf16_f32 v122, v122, v123
	v_cvt_pk_bf16_f32 v123, v166, v167
	global_store_dwordx4 v[164:165], v[120:123], off
	v_pk_mul_f32 v[116:117], v[158:159], v[116:117] op_sel_hi:[0,1]
	v_pk_mul_f32 v[118:119], v[158:159], v[118:119] op_sel_hi:[0,1]
	v_pk_mul_f32 v[120:121], v[158:159], v[110:111] op_sel_hi:[0,1]
	v_pk_mul_f32 v[110:111], v[158:159], v[108:109] op_sel_hi:[0,1]
	v_cvt_pk_bf16_f32 v108, v116, v117
	v_cvt_pk_bf16_f32 v109, v118, v119
	v_cvt_pk_bf16_f32 v110, v110, v111
	v_cvt_pk_bf16_f32 v111, v120, v121
	global_store_dwordx4 v[164:165], v[108:111], off offset:256
	v_pk_mul_f32 v[112:113], v[156:157], v[112:113] op_sel_hi:[0,1]
	v_pk_mul_f32 v[100:101], v[156:157], v[100:101] op_sel_hi:[0,1]
	v_or_b32_e32 v108, 16, v157
	v_mad_i64_i32 v[108:109], s[42:43], v108, s78, v[160:161]
	v_lshl_add_u64 v[108:109], v[108:109], 0, v[162:163]
	v_pk_mul_f32 v[110:111], v[156:157], v[114:115] op_sel_hi:[0,1]
	v_pk_mul_f32 v[114:115], v[156:157], v[106:107] op_sel_hi:[0,1]
	v_pk_mul_f32 v[106:107], v[156:157], v[104:105] op_sel_hi:[0,1]
	v_cvt_pk_bf16_f32 v104, v112, v113
	v_cvt_pk_bf16_f32 v105, v110, v111
	v_cvt_pk_bf16_f32 v106, v106, v107
	v_cvt_pk_bf16_f32 v107, v114, v115
	global_store_dwordx4 v[108:109], v[104:107], off
	v_pk_mul_f32 v[102:103], v[156:157], v[102:103] op_sel_hi:[0,1]
	v_pk_mul_f32 v[96:97], v[154:155], v[96:97] op_sel_hi:[0,1]
	v_pk_mul_f32 v[104:105], v[156:157], v[94:95] op_sel_hi:[0,1]
	v_pk_mul_f32 v[94:95], v[156:157], v[92:93] op_sel_hi:[0,1]
	v_cvt_pk_bf16_f32 v92, v100, v101
	v_cvt_pk_bf16_f32 v93, v102, v103
	v_cvt_pk_bf16_f32 v94, v94, v95
	v_cvt_pk_bf16_f32 v95, v104, v105
	global_store_dwordx4 v[108:109], v[92:95], off offset:256
	v_pk_mul_f32 v[84:85], v[154:155], v[84:85] op_sel_hi:[0,1]
	v_pk_mul_f32 v[86:87], v[154:155], v[86:87] op_sel_hi:[0,1]
	v_or_b32_e32 v92, 32, v157
	v_mad_i64_i32 v[92:93], s[42:43], v92, s78, v[160:161]
	v_lshl_add_u64 v[92:93], v[92:93], 0, v[162:163]
	v_pk_mul_f32 v[94:95], v[154:155], v[98:99] op_sel_hi:[0,1]
	v_pk_mul_f32 v[98:99], v[154:155], v[90:91] op_sel_hi:[0,1]
	v_pk_mul_f32 v[90:91], v[154:155], v[88:89] op_sel_hi:[0,1]
	v_cvt_pk_bf16_f32 v88, v96, v97
	v_cvt_pk_bf16_f32 v89, v94, v95
	v_cvt_pk_bf16_f32 v90, v90, v91
	v_cvt_pk_bf16_f32 v91, v98, v99
	global_store_dwordx4 v[92:93], v[88:91], off
	v_pk_mul_f32 v[80:81], v[152:153], v[80:81] op_sel_hi:[0,1]
	v_pk_mul_f32 v[68:69], v[152:153], v[68:69] op_sel_hi:[0,1]
	v_pk_mul_f32 v[88:89], v[154:155], v[78:79] op_sel_hi:[0,1]
	v_pk_mul_f32 v[78:79], v[154:155], v[76:77] op_sel_hi:[0,1]
	v_cvt_pk_bf16_f32 v76, v84, v85
	v_cvt_pk_bf16_f32 v77, v86, v87
	v_cvt_pk_bf16_f32 v78, v78, v79
	v_cvt_pk_bf16_f32 v79, v88, v89
	global_store_dwordx4 v[92:93], v[76:79], off offset:256
	v_pk_mul_f32 v[70:71], v[152:153], v[70:71] op_sel_hi:[0,1]
	v_pk_mul_f32 v[62:63], v[150:151], v[62:63] op_sel_hi:[0,1]
	v_or_b32_e32 v76, 48, v157
	v_mad_i64_i32 v[76:77], s[42:43], v76, s78, v[160:161]
	v_lshl_add_u64 v[76:77], v[76:77], 0, v[162:163]
	v_pk_mul_f32 v[78:79], v[152:153], v[82:83] op_sel_hi:[0,1]
	v_pk_mul_f32 v[82:83], v[152:153], v[74:75] op_sel_hi:[0,1]
	v_pk_mul_f32 v[74:75], v[152:153], v[72:73] op_sel_hi:[0,1]
	v_cvt_pk_bf16_f32 v72, v80, v81
	v_cvt_pk_bf16_f32 v73, v78, v79
	v_cvt_pk_bf16_f32 v74, v74, v75
	v_cvt_pk_bf16_f32 v75, v82, v83
	global_store_dwordx4 v[76:77], v[72:75], off
	v_pk_mul_f32 v[60:61], v[150:151], v[60:61] op_sel_hi:[0,1]
	v_pk_mul_f32 v[52:53], v[150:151], v[52:53] op_sel_hi:[0,1]
	v_pk_mul_f32 v[72:73], v[152:153], v[66:67] op_sel_hi:[0,1]
	v_pk_mul_f32 v[66:67], v[152:153], v[64:65] op_sel_hi:[0,1]
	v_cvt_pk_bf16_f32 v64, v68, v69
	v_cvt_pk_bf16_f32 v65, v70, v71
	v_cvt_pk_bf16_f32 v66, v66, v67
	v_cvt_pk_bf16_f32 v67, v72, v73
	global_store_dwordx4 v[76:77], v[64:67], off offset:256
	v_pk_mul_f32 v[54:55], v[150:151], v[54:55] op_sel_hi:[0,1]
	v_pk_mul_f32 v[48:49], v[140:141], v[48:49] op_sel_hi:[0,1]
	v_add_u32_e32 v64, 0x80, v157
	v_mad_i64_i32 v[64:65], s[42:43], v64, s78, v[160:161]
	v_lshl_add_u64 v[64:65], v[64:65], 0, v[162:163]
	v_pk_mul_f32 v[66:67], v[150:151], v[58:59] op_sel_hi:[0,1]
	v_pk_mul_f32 v[58:59], v[150:151], v[56:57] op_sel_hi:[0,1]
	v_cvt_pk_bf16_f32 v56, v60, v61
	v_cvt_pk_bf16_f32 v57, v62, v63
	v_cvt_pk_bf16_f32 v58, v58, v59
	v_cvt_pk_bf16_f32 v59, v66, v67
	global_store_dwordx4 v[64:65], v[56:59], off
	v_pk_mul_f32 v[36:37], v[140:141], v[36:37] op_sel_hi:[0,1]
	v_pk_mul_f32 v[38:39], v[140:141], v[38:39] op_sel_hi:[0,1]
	v_pk_mul_f32 v[56:57], v[150:151], v[46:47] op_sel_hi:[0,1]
	v_pk_mul_f32 v[46:47], v[150:151], v[44:45] op_sel_hi:[0,1]
	v_cvt_pk_bf16_f32 v44, v52, v53
	v_cvt_pk_bf16_f32 v45, v54, v55
	v_cvt_pk_bf16_f32 v46, v46, v47
	v_cvt_pk_bf16_f32 v47, v56, v57
	global_store_dwordx4 v[64:65], v[44:47], off offset:256
	v_pk_mul_f32 v[32:33], v[138:139], v[32:33] op_sel_hi:[0,1]
	v_pk_mul_f32 v[20:21], v[138:139], v[20:21] op_sel_hi:[0,1]
	v_add_u32_e32 v44, 0x90, v157
	v_mad_i64_i32 v[44:45], s[42:43], v44, s78, v[160:161]
	v_lshl_add_u64 v[44:45], v[44:45], 0, v[162:163]
	v_pk_mul_f32 v[46:47], v[140:141], v[50:51] op_sel_hi:[0,1]
	v_pk_mul_f32 v[50:51], v[140:141], v[42:43] op_sel_hi:[0,1]
	v_pk_mul_f32 v[42:43], v[140:141], v[40:41] op_sel_hi:[0,1]
	v_cvt_pk_bf16_f32 v40, v48, v49
	v_cvt_pk_bf16_f32 v41, v46, v47
	v_cvt_pk_bf16_f32 v42, v42, v43
	v_cvt_pk_bf16_f32 v43, v50, v51
	global_store_dwordx4 v[44:45], v[40:43], off
	v_pk_mul_f32 v[22:23], v[138:139], v[22:23] op_sel_hi:[0,1]
	v_pk_mul_f32 v[16:17], v[136:137], v[16:17] op_sel_hi:[0,1]
	v_pk_mul_f32 v[40:41], v[140:141], v[30:31] op_sel_hi:[0,1]
	v_pk_mul_f32 v[30:31], v[140:141], v[28:29] op_sel_hi:[0,1]
	v_cvt_pk_bf16_f32 v28, v36, v37
	v_cvt_pk_bf16_f32 v29, v38, v39
	v_cvt_pk_bf16_f32 v30, v30, v31
	v_cvt_pk_bf16_f32 v31, v40, v41
	global_store_dwordx4 v[44:45], v[28:31], off offset:256
	s_and_b64 vcc, s[8:9], exec
	v_pk_mul_f32 v[6:7], v[136:137], v[6:7] op_sel_hi:[0,1]
	v_add_u32_e32 v28, 0xa0, v157
	v_mad_i64_i32 v[28:29], s[42:43], v28, s78, v[160:161]
	v_lshl_add_u64 v[28:29], v[28:29], 0, v[162:163]
	v_pk_mul_f32 v[30:31], v[138:139], v[34:35] op_sel_hi:[0,1]
	v_pk_mul_f32 v[34:35], v[138:139], v[26:27] op_sel_hi:[0,1]
	v_pk_mul_f32 v[26:27], v[138:139], v[24:25] op_sel_hi:[0,1]
	v_cvt_pk_bf16_f32 v24, v32, v33
	v_cvt_pk_bf16_f32 v25, v30, v31
	v_cvt_pk_bf16_f32 v26, v26, v27
	v_cvt_pk_bf16_f32 v27, v34, v35
	global_store_dwordx4 v[28:29], v[24:27], off
	v_pk_mul_f32 v[4:5], v[136:137], v[4:5] op_sel_hi:[0,1]
	s_nop 0
	v_pk_mul_f32 v[24:25], v[138:139], v[14:15] op_sel_hi:[0,1]
	v_pk_mul_f32 v[14:15], v[138:139], v[12:13] op_sel_hi:[0,1]
	v_cvt_pk_bf16_f32 v12, v20, v21
	v_cvt_pk_bf16_f32 v13, v22, v23
	v_cvt_pk_bf16_f32 v14, v14, v15
	v_cvt_pk_bf16_f32 v15, v24, v25
	global_store_dwordx4 v[28:29], v[12:15], off offset:256
	s_nop 1
	v_add_u32_e32 v12, 0xb0, v157
	v_mad_i64_i32 v[12:13], s[42:43], v12, s78, v[160:161]
	v_lshl_add_u64 v[12:13], v[12:13], 0, v[162:163]
	v_pk_mul_f32 v[14:15], v[136:137], v[18:19] op_sel_hi:[0,1]
	v_pk_mul_f32 v[18:19], v[136:137], v[10:11] op_sel_hi:[0,1]
	v_pk_mul_f32 v[10:11], v[136:137], v[8:9] op_sel_hi:[0,1]
	v_cvt_pk_bf16_f32 v8, v16, v17
	v_cvt_pk_bf16_f32 v9, v14, v15
	v_cvt_pk_bf16_f32 v10, v10, v11
	v_cvt_pk_bf16_f32 v11, v18, v19
	global_store_dwordx4 v[12:13], v[8:11], off
	s_mov_b64 s[42:43], -1
	s_nop 0
	v_pk_mul_f32 v[8:9], v[136:137], v[2:3] op_sel_hi:[0,1]
	v_pk_mul_f32 v[2:3], v[136:137], v[0:1] op_sel_hi:[0,1]
	v_cvt_pk_bf16_f32 v0, v4, v5
	v_cvt_pk_bf16_f32 v1, v6, v7
	v_cvt_pk_bf16_f32 v2, v2, v3
	v_cvt_pk_bf16_f32 v3, v8, v9
	global_store_dwordx4 v[12:13], v[0:3], off offset:256
	s_cbranch_vccz .LBB0_295
	s_nop 0
	v_lshl_add_u32 v0, s79, 8, v137
	v_ashrrev_i32_e32 v1, 31, v0
	v_lshl_add_u64 v[0:1], v[0:1], 2, s[72:73]
	global_load_dword v158, v[0:1], off
	global_load_dword v156, v[0:1], off offset:64
	global_load_dword v154, v[0:1], off offset:128
	global_load_dword v152, v[0:1], off offset:192
	global_load_dword v150, v[0:1], off offset:512
	global_load_dword v140, v[0:1], off offset:576
	global_load_dword v138, v[0:1], off offset:640
	global_load_dword v136, v[0:1], off offset:704
	s_mov_b64 s[42:43], 0
	s_branch .LBB0_295

.LBB0_325:
	ds_read_b128 v[160:163], v151
	ds_read_b128 v[164:167], v151 offset:1024
	ds_read_b128 v[168:171], v151 offset:2048
	ds_read_b128 v[176:179], v151 offset:3072
	s_add_u32 s48, s46, 0x100
	s_addc_u32 s49, s47, 0
	s_cmp_eq_u32 s91, 4
	s_cselect_b32 s53, s43, s49
	s_cselect_b32 s52, s42, s48
	s_cselect_b32 s51, s41, s90
	s_cselect_b32 s50, s62, s63
	v_lshl_add_u64 v[214:215], s[46:47], 0, v[142:143]
	s_add_i32 m0, s55, 0xc000
	ds_read_b128 v[180:183], v153
	ds_read_b128 v[186:189], v153 offset:1024
	ds_read_b128 v[190:193], v153 offset:2048
	ds_read_b128 v[194:197], v153 offset:3072
	ds_read_b128 v[198:201], v153 offset:4096
	ds_read_b128 v[202:205], v153 offset:5120
	ds_read_b128 v[206:209], v153 offset:6144
	ds_read_b128 v[210:213], v153 offset:7168
	global_load_lds_dwordx4 v[214:215], off
	s_add_i32 m0, s55, 0xe000
	v_lshl_add_u64 v[214:215], s[46:47], 0, v[144:145]
	global_load_lds_dwordx4 v[214:215], off
	s_waitcnt lgkmcnt(8)
	s_barrier
	s_waitcnt lgkmcnt(0)
	v_mfma_f32_16x16x32_bf16 v[124:127], v[160:163], v[180:183], v[124:127]
	v_mfma_f32_16x16x32_bf16 v[124:127], v[164:167], v[186:189], v[124:127]
	v_mfma_f32_16x16x32_bf16 v[120:123], v[168:171], v[180:183], v[120:123]
	v_mfma_f32_16x16x32_bf16 v[120:123], v[176:179], v[186:189], v[120:123]
	v_mfma_f32_16x16x32_bf16 v[108:111], v[160:163], v[190:193], v[108:111]
	v_mfma_f32_16x16x32_bf16 v[108:111], v[164:167], v[194:197], v[108:111]
	v_mfma_f32_16x16x32_bf16 v[104:107], v[168:171], v[190:193], v[104:107]
	v_mfma_f32_16x16x32_bf16 v[104:107], v[176:179], v[194:197], v[104:107]
	v_mfma_f32_16x16x32_bf16 v[92:95], v[160:163], v[198:201], v[92:95]
	v_mfma_f32_16x16x32_bf16 v[92:95], v[164:167], v[202:205], v[92:95]
	v_mfma_f32_16x16x32_bf16 v[88:91], v[168:171], v[198:201], v[88:91]
	v_mfma_f32_16x16x32_bf16 v[88:91], v[176:179], v[202:205], v[88:91]
	v_mfma_f32_16x16x32_bf16 v[76:79], v[160:163], v[206:209], v[76:79]
	v_mfma_f32_16x16x32_bf16 v[76:79], v[164:167], v[210:213], v[76:79]
	v_mfma_f32_16x16x32_bf16 v[72:75], v[168:171], v[206:209], v[72:75]
	v_mfma_f32_16x16x32_bf16 v[72:75], v[176:179], v[210:213], v[72:75]
	s_barrier
	s_add_i32 s46, s81, s54
	v_lshl_add_u64 v[230:231], s[50:51], 0, v[130:131]
	s_mov_b32 m0, s46
	ds_read_b128 v[214:217], v155
	ds_read_b128 v[218:221], v155 offset:1024
	ds_read_b128 v[222:225], v155 offset:2048
	ds_read_b128 v[226:229], v155 offset:3072
	global_load_lds_dwordx4 v[230:231], off
	s_add_i32 m0, s46, 0x2000
	v_lshl_add_u64 v[232:233], s[50:51], 0, v[134:135]
	global_load_lds_dwordx4 v[232:233], off
	s_barrier
	s_waitcnt lgkmcnt(0)
	v_mfma_f32_16x16x32_bf16 v[116:119], v[214:217], v[180:183], v[116:119]
	v_mfma_f32_16x16x32_bf16 v[116:119], v[218:221], v[186:189], v[116:119]
	v_mfma_f32_16x16x32_bf16 v[112:115], v[222:225], v[180:183], v[112:115]
	v_mfma_f32_16x16x32_bf16 v[112:115], v[226:229], v[186:189], v[112:115]
	v_mfma_f32_16x16x32_bf16 v[100:103], v[214:217], v[190:193], v[100:103]
	v_mfma_f32_16x16x32_bf16 v[100:103], v[218:221], v[194:197], v[100:103]
	v_mfma_f32_16x16x32_bf16 v[96:99], v[222:225], v[190:193], v[96:99]
	v_mfma_f32_16x16x32_bf16 v[96:99], v[226:229], v[194:197], v[96:99]
	v_mfma_f32_16x16x32_bf16 v[84:87], v[214:217], v[198:201], v[84:87]
	v_mfma_f32_16x16x32_bf16 v[84:87], v[218:221], v[202:205], v[84:87]
	v_mfma_f32_16x16x32_bf16 v[80:83], v[222:225], v[198:201], v[80:83]
	v_mfma_f32_16x16x32_bf16 v[80:83], v[226:229], v[202:205], v[80:83]
	v_mfma_f32_16x16x32_bf16 v[68:71], v[214:217], v[206:209], v[68:71]
	v_mfma_f32_16x16x32_bf16 v[68:71], v[218:221], v[210:213], v[68:71]
	v_mfma_f32_16x16x32_bf16 v[64:67], v[222:225], v[206:209], v[64:67]
	v_mfma_f32_16x16x32_bf16 v[64:67], v[226:229], v[210:213], v[64:67]
	s_mov_b32 m0, s55
	v_lshl_add_u64 v[234:235], s[52:53], 0, v[128:129]
	s_barrier
	ds_read_b128 v[180:183], v153 offset:16384
	ds_read_b128 v[186:189], v153 offset:17408
	ds_read_b128 v[190:193], v153 offset:18432
	ds_read_b128 v[194:197], v153 offset:19456
	ds_read_b128 v[198:201], v153 offset:20480
	ds_read_b128 v[202:205], v153 offset:21504
	ds_read_b128 v[206:209], v153 offset:22528
	ds_read_b128 v[210:213], v153 offset:23552
	global_load_lds_dwordx4 v[234:235], off
	s_mov_b32 m0, s61
	v_lshl_add_u64 v[236:237], s[52:53], 0, v[132:133]
	global_load_lds_dwordx4 v[236:237], off
	s_barrier
	s_waitcnt lgkmcnt(0)
	v_mfma_f32_16x16x32_bf16 v[60:63], v[160:163], v[180:183], v[60:63]
	v_mfma_f32_16x16x32_bf16 v[60:63], v[164:167], v[186:189], v[60:63]
	v_mfma_f32_16x16x32_bf16 v[56:59], v[168:171], v[180:183], v[56:59]
	v_mfma_f32_16x16x32_bf16 v[56:59], v[176:179], v[186:189], v[56:59]
	v_mfma_f32_16x16x32_bf16 v[48:51], v[160:163], v[190:193], v[48:51]
	v_mfma_f32_16x16x32_bf16 v[48:51], v[164:167], v[194:197], v[48:51]
	v_mfma_f32_16x16x32_bf16 v[40:43], v[168:171], v[190:193], v[40:43]
	v_mfma_f32_16x16x32_bf16 v[40:43], v[176:179], v[194:197], v[40:43]
	v_mfma_f32_16x16x32_bf16 v[32:35], v[160:163], v[198:201], v[32:35]
	v_mfma_f32_16x16x32_bf16 v[32:35], v[164:167], v[202:205], v[32:35]
	v_mfma_f32_16x16x32_bf16 v[24:27], v[168:171], v[198:201], v[24:27]
	v_mfma_f32_16x16x32_bf16 v[24:27], v[176:179], v[202:205], v[24:27]
	v_mfma_f32_16x16x32_bf16 v[16:19], v[160:163], v[206:209], v[16:19]
	v_mfma_f32_16x16x32_bf16 v[16:19], v[164:167], v[210:213], v[16:19]
	v_mfma_f32_16x16x32_bf16 v[8:11], v[168:171], v[206:209], v[8:11]
	v_mfma_f32_16x16x32_bf16 v[8:11], v[176:179], v[210:213], v[8:11]
	s_barrier
	s_add_u32 s46, s50, 0x20000
	s_addc_u32 s47, s51, 0
	s_add_i32 s92, s82, s54
	s_mov_b32 m0, s92
	v_lshl_add_u64 v[160:161], s[46:47], 0, v[130:131]
	global_load_lds_dwordx4 v[160:161], off
	s_add_i32 m0, s92, 0x2000
	v_lshl_add_u64 v[160:161], s[46:47], 0, v[134:135]
	global_load_lds_dwordx4 v[160:161], off
	s_waitcnt vmcnt(6)
	s_barrier
	v_mfma_f32_16x16x32_bf16 v[52:55], v[214:217], v[180:183], v[52:55]
	v_mfma_f32_16x16x32_bf16 v[52:55], v[218:221], v[186:189], v[52:55]
	v_mfma_f32_16x16x32_bf16 v[44:47], v[222:225], v[180:183], v[44:47]
	v_mfma_f32_16x16x32_bf16 v[44:47], v[226:229], v[186:189], v[44:47]
	v_mfma_f32_16x16x32_bf16 v[36:39], v[214:217], v[190:193], v[36:39]
	v_mfma_f32_16x16x32_bf16 v[36:39], v[218:221], v[194:197], v[36:39]
	v_mfma_f32_16x16x32_bf16 v[28:31], v[222:225], v[190:193], v[28:31]
	v_mfma_f32_16x16x32_bf16 v[28:31], v[226:229], v[194:197], v[28:31]
	v_mfma_f32_16x16x32_bf16 v[20:23], v[214:217], v[198:201], v[20:23]
	v_mfma_f32_16x16x32_bf16 v[20:23], v[218:221], v[202:205], v[20:23]
	v_mfma_f32_16x16x32_bf16 v[12:15], v[222:225], v[198:201], v[12:15]
	v_mfma_f32_16x16x32_bf16 v[12:15], v[226:229], v[202:205], v[12:15]
	v_mfma_f32_16x16x32_bf16 v[4:7], v[214:217], v[206:209], v[4:7]
	v_mfma_f32_16x16x32_bf16 v[4:7], v[218:221], v[210:213], v[4:7]
	v_mfma_f32_16x16x32_bf16 v[0:3], v[222:225], v[206:209], v[0:3]
	v_mfma_f32_16x16x32_bf16 v[0:3], v[226:229], v[210:213], v[0:3]
	s_add_i32 s92, 0, 0x18000
	v_add_u32_e32 v157, s92, v139
	s_barrier
	ds_read_b128 v[160:163], v157
	ds_read_b128 v[164:167], v157 offset:1024
	ds_read_b128 v[168:171], v157 offset:2048
	ds_read_b128 v[176:179], v157 offset:3072
	s_add_u32 s46, s52, 0x170000
	s_addc_u32 s47, s53, 0
	s_mov_b32 m0, s74
	v_lshl_add_u64 v[214:215], s[46:47], 0, v[128:129]
	ds_read_b128 v[180:183], v153 offset:32768
	ds_read_b128 v[186:189], v153 offset:33792
	ds_read_b128 v[190:193], v153 offset:34816
	ds_read_b128 v[194:197], v153 offset:35840
	ds_read_b128 v[198:201], v153 offset:36864
	ds_read_b128 v[202:205], v153 offset:37888
	ds_read_b128 v[206:209], v153 offset:38912
	ds_read_b128 v[210:213], v153 offset:39936
	global_load_lds_dwordx4 v[214:215], off
	s_mov_b32 m0, s75
	v_lshl_add_u64 v[214:215], s[46:47], 0, v[132:133]
	global_load_lds_dwordx4 v[214:215], off
	s_waitcnt lgkmcnt(8)
	s_barrier
	s_waitcnt lgkmcnt(0)
	v_mfma_f32_16x16x32_bf16 v[124:127], v[160:163], v[180:183], v[124:127]
	v_mfma_f32_16x16x32_bf16 v[124:127], v[164:167], v[186:189], v[124:127]
	v_mfma_f32_16x16x32_bf16 v[120:123], v[168:171], v[180:183], v[120:123]
	v_mfma_f32_16x16x32_bf16 v[120:123], v[176:179], v[186:189], v[120:123]
	v_mfma_f32_16x16x32_bf16 v[108:111], v[160:163], v[190:193], v[108:111]
	v_mfma_f32_16x16x32_bf16 v[108:111], v[164:167], v[194:197], v[108:111]
	v_mfma_f32_16x16x32_bf16 v[104:107], v[168:171], v[190:193], v[104:107]
	v_mfma_f32_16x16x32_bf16 v[104:107], v[176:179], v[194:197], v[104:107]
	v_mfma_f32_16x16x32_bf16 v[92:95], v[160:163], v[198:201], v[92:95]
	v_mfma_f32_16x16x32_bf16 v[92:95], v[164:167], v[202:205], v[92:95]
	v_mfma_f32_16x16x32_bf16 v[88:91], v[168:171], v[198:201], v[88:91]
	v_mfma_f32_16x16x32_bf16 v[88:91], v[176:179], v[202:205], v[88:91]
	v_mfma_f32_16x16x32_bf16 v[76:79], v[160:163], v[206:209], v[76:79]
	v_mfma_f32_16x16x32_bf16 v[76:79], v[164:167], v[210:213], v[76:79]
	v_mfma_f32_16x16x32_bf16 v[72:75], v[168:171], v[206:209], v[72:75]
	v_mfma_f32_16x16x32_bf16 v[72:75], v[176:179], v[210:213], v[72:75]
	s_barrier
	s_add_i32 s52, 0, 0x1c000
	s_add_i32 s46, s92, s54
	v_add_u32_e32 v157, s52, v139
	v_lshl_add_u64 v[230:231], v[230:231], 0, s[10:11]
	s_mov_b32 m0, s46
	ds_read_b128 v[214:217], v157
	ds_read_b128 v[218:221], v157 offset:1024
	ds_read_b128 v[222:225], v157 offset:2048
	ds_read_b128 v[226:229], v157 offset:3072
	global_load_lds_dwordx4 v[230:231], off
	s_add_i32 m0, s46, 0x2000
	v_lshl_add_u64 v[230:231], v[232:233], 0, s[10:11]
	global_load_lds_dwordx4 v[230:231], off
	s_barrier
	s_waitcnt lgkmcnt(0)
	v_mfma_f32_16x16x32_bf16 v[116:119], v[214:217], v[180:183], v[116:119]
	v_mfma_f32_16x16x32_bf16 v[116:119], v[218:221], v[186:189], v[116:119]
	v_mfma_f32_16x16x32_bf16 v[112:115], v[222:225], v[180:183], v[112:115]
	v_mfma_f32_16x16x32_bf16 v[112:115], v[226:229], v[186:189], v[112:115]
	v_mfma_f32_16x16x32_bf16 v[100:103], v[214:217], v[190:193], v[100:103]
	v_mfma_f32_16x16x32_bf16 v[100:103], v[218:221], v[194:197], v[100:103]
	v_mfma_f32_16x16x32_bf16 v[96:99], v[222:225], v[190:193], v[96:99]
	v_mfma_f32_16x16x32_bf16 v[96:99], v[226:229], v[194:197], v[96:99]
	v_mfma_f32_16x16x32_bf16 v[84:87], v[214:217], v[198:201], v[84:87]
	v_mfma_f32_16x16x32_bf16 v[84:87], v[218:221], v[202:205], v[84:87]
	v_mfma_f32_16x16x32_bf16 v[80:83], v[222:225], v[198:201], v[80:83]
	v_mfma_f32_16x16x32_bf16 v[80:83], v[226:229], v[202:205], v[80:83]
	v_mfma_f32_16x16x32_bf16 v[68:71], v[214:217], v[206:209], v[68:71]
	v_mfma_f32_16x16x32_bf16 v[68:71], v[218:221], v[210:213], v[68:71]
	v_mfma_f32_16x16x32_bf16 v[64:67], v[222:225], v[206:209], v[64:67]
	v_mfma_f32_16x16x32_bf16 v[64:67], v[226:229], v[210:213], v[64:67]
	s_mov_b32 m0, s77
	v_lshl_add_u64 v[230:231], v[234:235], 0, s[10:11]
	s_barrier
	ds_read_b128 v[180:183], v153 offset:49152
	ds_read_b128 v[186:189], v153 offset:50176
	ds_read_b128 v[190:193], v153 offset:51200
	ds_read_b128 v[194:197], v153 offset:52224
	ds_read_b128 v[198:201], v153 offset:53248
	ds_read_b128 v[202:205], v153 offset:54272
	ds_read_b128 v[206:209], v153 offset:55296
	ds_read_b128 v[210:213], v153 offset:56320
	global_load_lds_dwordx4 v[230:231], off
	s_mov_b32 m0, s78
	v_lshl_add_u64 v[230:231], v[236:237], 0, s[10:11]
	global_load_lds_dwordx4 v[230:231], off
	s_barrier
	s_waitcnt lgkmcnt(0)
	v_mfma_f32_16x16x32_bf16 v[60:63], v[160:163], v[180:183], v[60:63]
	v_mfma_f32_16x16x32_bf16 v[60:63], v[164:167], v[186:189], v[60:63]
	v_mfma_f32_16x16x32_bf16 v[56:59], v[168:171], v[180:183], v[56:59]
	v_mfma_f32_16x16x32_bf16 v[56:59], v[176:179], v[186:189], v[56:59]
	v_mfma_f32_16x16x32_bf16 v[48:51], v[160:163], v[190:193], v[48:51]
	v_mfma_f32_16x16x32_bf16 v[48:51], v[164:167], v[194:197], v[48:51]
	v_mfma_f32_16x16x32_bf16 v[40:43], v[168:171], v[190:193], v[40:43]
	v_mfma_f32_16x16x32_bf16 v[40:43], v[176:179], v[194:197], v[40:43]
	v_mfma_f32_16x16x32_bf16 v[32:35], v[160:163], v[198:201], v[32:35]
	v_mfma_f32_16x16x32_bf16 v[32:35], v[164:167], v[202:205], v[32:35]
	v_mfma_f32_16x16x32_bf16 v[24:27], v[168:171], v[198:201], v[24:27]
	v_mfma_f32_16x16x32_bf16 v[24:27], v[176:179], v[202:205], v[24:27]
	v_mfma_f32_16x16x32_bf16 v[16:19], v[160:163], v[206:209], v[16:19]
	v_mfma_f32_16x16x32_bf16 v[16:19], v[164:167], v[210:213], v[16:19]
	v_mfma_f32_16x16x32_bf16 v[8:11], v[168:171], v[206:209], v[8:11]
	v_mfma_f32_16x16x32_bf16 v[8:11], v[176:179], v[210:213], v[8:11]
	s_barrier
	s_add_u32 s46, s50, 0x20080
	s_addc_u32 s47, s51, 0
	s_add_i32 s50, s52, s54
	s_mov_b32 m0, s50
	v_lshl_add_u64 v[160:161], s[46:47], 0, v[130:131]
	global_load_lds_dwordx4 v[160:161], off
	s_add_i32 m0, s50, 0x2000
	v_lshl_add_u64 v[160:161], s[46:47], 0, v[134:135]
	global_load_lds_dwordx4 v[160:161], off
	s_waitcnt vmcnt(6)
	s_barrier
	v_mfma_f32_16x16x32_bf16 v[52:55], v[214:217], v[180:183], v[52:55]
	v_mfma_f32_16x16x32_bf16 v[52:55], v[218:221], v[186:189], v[52:55]
	v_mfma_f32_16x16x32_bf16 v[44:47], v[222:225], v[180:183], v[44:47]
	v_mfma_f32_16x16x32_bf16 v[44:47], v[226:229], v[186:189], v[44:47]
	v_mfma_f32_16x16x32_bf16 v[36:39], v[214:217], v[190:193], v[36:39]
	v_mfma_f32_16x16x32_bf16 v[36:39], v[218:221], v[194:197], v[36:39]
	v_mfma_f32_16x16x32_bf16 v[28:31], v[222:225], v[190:193], v[28:31]
	v_mfma_f32_16x16x32_bf16 v[28:31], v[226:229], v[194:197], v[28:31]
	v_mfma_f32_16x16x32_bf16 v[20:23], v[214:217], v[198:201], v[20:23]
	v_mfma_f32_16x16x32_bf16 v[20:23], v[218:221], v[202:205], v[20:23]
	v_mfma_f32_16x16x32_bf16 v[12:15], v[222:225], v[198:201], v[12:15]
	v_mfma_f32_16x16x32_bf16 v[12:15], v[226:229], v[202:205], v[12:15]
	v_mfma_f32_16x16x32_bf16 v[4:7], v[214:217], v[206:209], v[4:7]
	v_mfma_f32_16x16x32_bf16 v[4:7], v[218:221], v[210:213], v[4:7]
	v_mfma_f32_16x16x32_bf16 v[0:3], v[222:225], v[206:209], v[0:3]
	v_mfma_f32_16x16x32_bf16 v[0:3], v[226:229], v[210:213], v[0:3]
	s_add_i32 s91, s91, 2
	s_add_u32 s63, s63, 0x100
	s_addc_u32 s90, s90, 0
	s_cmp_gt_u32 s91, 5
	s_mov_b64 s[46:47], s[48:49]
	s_barrier
	s_cbranch_scc0 .LBB0_325
	v_lshl_add_u32 v162, s88, 8, v137
	v_lshl_or_b32 v160, s89, 8, v141
	v_ashrrev_i32_e32 v163, 31, v162
	v_ashrrev_i32_e32 v161, 31, v160
	v_lshlrev_b64 v[164:165], 14, v[162:163]
	v_lshl_add_u64 v[164:165], s[56:57], 0, v[164:165]
	v_lshlrev_b64 v[166:167], 1, v[160:161]
	v_lshl_add_u64 v[160:161], v[164:165], 0, v[166:167]
	s_waitcnt vmcnt(6)
	v_pk_mul_f32 v[126:127], v[158:159], v[126:127] op_sel_hi:[0,1]
	v_pk_mul_f32 v[124:125], v[158:159], v[124:125] op_sel_hi:[0,1]
	v_pk_mul_f32 v[164:165], v[158:159], v[122:123] op_sel_hi:[0,1]
	v_pk_mul_f32 v[122:123], v[158:159], v[120:121] op_sel_hi:[0,1]
	v_cvt_pk_bf16_f32 v120, v124, v125
	v_cvt_pk_bf16_f32 v121, v126, v127
	v_cvt_pk_bf16_f32 v122, v122, v123
	v_cvt_pk_bf16_f32 v123, v164, v165
	global_store_dwordx4 v[160:161], v[120:123], off
	v_pk_mul_f32 v[116:117], v[158:159], v[116:117] op_sel_hi:[0,1]
	v_pk_mul_f32 v[118:119], v[158:159], v[118:119] op_sel_hi:[0,1]
	v_pk_mul_f32 v[120:121], v[158:159], v[114:115] op_sel_hi:[0,1]
	v_pk_mul_f32 v[114:115], v[158:159], v[112:113] op_sel_hi:[0,1]
	v_cvt_pk_bf16_f32 v112, v116, v117
	v_cvt_pk_bf16_f32 v113, v118, v119
	v_cvt_pk_bf16_f32 v114, v114, v115
	v_cvt_pk_bf16_f32 v115, v120, v121
	global_store_dwordx4 v[160:161], v[112:115], off offset:256
	v_pk_mul_f32 v[110:111], v[156:157], v[110:111] op_sel_hi:[0,1]
	v_pk_mul_f32 v[108:109], v[156:157], v[108:109] op_sel_hi:[0,1]
	v_or_b32_e32 v112, 16, v162
	v_ashrrev_i32_e32 v113, 31, v112
	v_lshlrev_b64 v[112:113], 14, v[112:113]
	v_lshl_add_u64 v[112:113], s[56:57], 0, v[112:113]
	v_lshl_add_u64 v[112:113], v[112:113], 0, v[166:167]
	v_pk_mul_f32 v[114:115], v[156:157], v[106:107] op_sel_hi:[0,1]
	v_pk_mul_f32 v[106:107], v[156:157], v[104:105] op_sel_hi:[0,1]
	v_cvt_pk_bf16_f32 v104, v108, v109
	v_cvt_pk_bf16_f32 v105, v110, v111
	v_cvt_pk_bf16_f32 v106, v106, v107
	v_cvt_pk_bf16_f32 v107, v114, v115
	global_store_dwordx4 v[112:113], v[104:107], off
	v_pk_mul_f32 v[100:101], v[156:157], v[100:101] op_sel_hi:[0,1]
	v_pk_mul_f32 v[102:103], v[156:157], v[102:103] op_sel_hi:[0,1]
	v_pk_mul_f32 v[104:105], v[156:157], v[98:99] op_sel_hi:[0,1]
	v_pk_mul_f32 v[98:99], v[156:157], v[96:97] op_sel_hi:[0,1]
	v_cvt_pk_bf16_f32 v96, v100, v101
	v_cvt_pk_bf16_f32 v97, v102, v103
	v_cvt_pk_bf16_f32 v98, v98, v99
	v_cvt_pk_bf16_f32 v99, v104, v105
	global_store_dwordx4 v[112:113], v[96:99], off offset:256
	v_pk_mul_f32 v[94:95], v[154:155], v[94:95] op_sel_hi:[0,1]
	v_pk_mul_f32 v[92:93], v[154:155], v[92:93] op_sel_hi:[0,1]
	v_or_b32_e32 v96, 32, v162
	v_ashrrev_i32_e32 v97, 31, v96
	v_lshlrev_b64 v[96:97], 14, v[96:97]
	v_lshl_add_u64 v[96:97], s[56:57], 0, v[96:97]
	v_lshl_add_u64 v[96:97], v[96:97], 0, v[166:167]
	v_pk_mul_f32 v[98:99], v[154:155], v[90:91] op_sel_hi:[0,1]
	v_pk_mul_f32 v[90:91], v[154:155], v[88:89] op_sel_hi:[0,1]
	v_cvt_pk_bf16_f32 v88, v92, v93
	v_cvt_pk_bf16_f32 v89, v94, v95
	v_cvt_pk_bf16_f32 v90, v90, v91
	v_cvt_pk_bf16_f32 v91, v98, v99
	global_store_dwordx4 v[96:97], v[88:91], off
	v_pk_mul_f32 v[84:85], v[154:155], v[84:85] op_sel_hi:[0,1]
	v_pk_mul_f32 v[86:87], v[154:155], v[86:87] op_sel_hi:[0,1]
	v_pk_mul_f32 v[88:89], v[154:155], v[82:83] op_sel_hi:[0,1]
	v_pk_mul_f32 v[82:83], v[154:155], v[80:81] op_sel_hi:[0,1]
	v_cvt_pk_bf16_f32 v80, v84, v85
	v_cvt_pk_bf16_f32 v81, v86, v87
	v_cvt_pk_bf16_f32 v82, v82, v83
	v_cvt_pk_bf16_f32 v83, v88, v89
	global_store_dwordx4 v[96:97], v[80:83], off offset:256
	v_pk_mul_f32 v[78:79], v[152:153], v[78:79] op_sel_hi:[0,1]
	v_pk_mul_f32 v[76:77], v[152:153], v[76:77] op_sel_hi:[0,1]
	v_or_b32_e32 v80, 48, v162
	v_ashrrev_i32_e32 v81, 31, v80
	v_lshlrev_b64 v[80:81], 14, v[80:81]
	v_lshl_add_u64 v[80:81], s[56:57], 0, v[80:81]
	v_lshl_add_u64 v[80:81], v[80:81], 0, v[166:167]
	v_pk_mul_f32 v[82:83], v[152:153], v[74:75] op_sel_hi:[0,1]
	v_pk_mul_f32 v[74:75], v[152:153], v[72:73] op_sel_hi:[0,1]
	v_cvt_pk_bf16_f32 v72, v76, v77
	v_cvt_pk_bf16_f32 v73, v78, v79
	v_cvt_pk_bf16_f32 v74, v74, v75
	v_cvt_pk_bf16_f32 v75, v82, v83
	global_store_dwordx4 v[80:81], v[72:75], off
	v_pk_mul_f32 v[70:71], v[152:153], v[70:71] op_sel_hi:[0,1]
	v_pk_mul_f32 v[68:69], v[152:153], v[68:69] op_sel_hi:[0,1]
	v_pk_mul_f32 v[72:73], v[152:153], v[66:67] op_sel_hi:[0,1]
	v_pk_mul_f32 v[66:67], v[152:153], v[64:65] op_sel_hi:[0,1]
	v_cvt_pk_bf16_f32 v64, v68, v69
	v_cvt_pk_bf16_f32 v65, v70, v71
	v_cvt_pk_bf16_f32 v66, v66, v67
	v_cvt_pk_bf16_f32 v67, v72, v73
	v_pk_mul_f32 v[60:61], v[150:151], v[60:61] op_sel_hi:[0,1]
	global_store_dwordx4 v[80:81], v[64:67], off offset:256
	v_pk_mul_f32 v[62:63], v[150:151], v[62:63] op_sel_hi:[0,1]
	s_mov_b64 s[46:47], 0x200000
	v_pk_mul_f32 v[66:67], v[150:151], v[58:59] op_sel_hi:[0,1]
	v_pk_mul_f32 v[58:59], v[150:151], v[56:57] op_sel_hi:[0,1]
	v_cvt_pk_bf16_f32 v56, v60, v61
	v_add_co_u32_e32 v60, vcc, s83, v160
	v_cvt_pk_bf16_f32 v57, v62, v63
	v_cvt_pk_bf16_f32 v58, v58, v59
	v_cvt_pk_bf16_f32 v59, v66, v67
	v_lshl_add_u64 v[64:65], v[160:161], 0, s[46:47]
	s_nop 0
	v_addc_co_u32_e32 v61, vcc, 0, v161, vcc
	global_store_dwordx4 v[60:61], v[56:59], off
	v_pk_mul_f32 v[54:55], v[150:151], v[54:55] op_sel_hi:[0,1]
	v_pk_mul_f32 v[52:53], v[150:151], v[52:53] op_sel_hi:[0,1]
	v_pk_mul_f32 v[56:57], v[150:151], v[46:47] op_sel_hi:[0,1]
	v_pk_mul_f32 v[46:47], v[150:151], v[44:45] op_sel_hi:[0,1]
	v_cvt_pk_bf16_f32 v44, v52, v53
	v_cvt_pk_bf16_f32 v45, v54, v55
	v_cvt_pk_bf16_f32 v46, v46, v47
	v_cvt_pk_bf16_f32 v47, v56, v57
	global_store_dwordx4 v[64:65], v[44:47], off offset:256
	v_pk_mul_f32 v[48:49], v[140:141], v[48:49] op_sel_hi:[0,1]
	v_pk_mul_f32 v[38:39], v[140:141], v[38:39] op_sel_hi:[0,1]
	v_pk_mul_f32 v[46:47], v[140:141], v[50:51] op_sel_hi:[0,1]
	v_pk_mul_f32 v[50:51], v[140:141], v[42:43] op_sel_hi:[0,1]
	v_pk_mul_f32 v[42:43], v[140:141], v[40:41] op_sel_hi:[0,1]
	v_cvt_pk_bf16_f32 v40, v48, v49
	v_cvt_pk_bf16_f32 v41, v46, v47
	v_add_co_u32_e32 v46, vcc, s84, v160
	v_cvt_pk_bf16_f32 v42, v42, v43
	v_cvt_pk_bf16_f32 v43, v50, v51
	v_lshl_add_u64 v[44:45], v[160:161], 0, s[30:31]
	s_nop 0
	v_addc_co_u32_e32 v47, vcc, 0, v161, vcc
	global_store_dwordx4 v[46:47], v[40:43], off
	v_pk_mul_f32 v[36:37], v[140:141], v[36:37] op_sel_hi:[0,1]
	v_pk_mul_f32 v[32:33], v[138:139], v[32:33] op_sel_hi:[0,1]
	v_pk_mul_f32 v[40:41], v[140:141], v[30:31] op_sel_hi:[0,1]
	v_pk_mul_f32 v[30:31], v[140:141], v[28:29] op_sel_hi:[0,1]
	v_cvt_pk_bf16_f32 v28, v36, v37
	v_cvt_pk_bf16_f32 v29, v38, v39
	v_cvt_pk_bf16_f32 v30, v30, v31
	v_cvt_pk_bf16_f32 v31, v40, v41
	global_store_dwordx4 v[44:45], v[28:31], off offset:256
	v_pk_mul_f32 v[22:23], v[138:139], v[22:23] op_sel_hi:[0,1]
	v_pk_mul_f32 v[20:21], v[138:139], v[20:21] op_sel_hi:[0,1]
	v_pk_mul_f32 v[30:31], v[138:139], v[34:35] op_sel_hi:[0,1]
	v_pk_mul_f32 v[34:35], v[138:139], v[26:27] op_sel_hi:[0,1]
	v_pk_mul_f32 v[26:27], v[138:139], v[24:25] op_sel_hi:[0,1]
	v_cvt_pk_bf16_f32 v24, v32, v33
	v_cvt_pk_bf16_f32 v25, v30, v31
	v_add_co_u32_e32 v30, vcc, s85, v160
	v_cvt_pk_bf16_f32 v26, v26, v27
	v_cvt_pk_bf16_f32 v27, v34, v35
	v_lshl_add_u64 v[28:29], v[160:161], 0, s[36:37]
	s_nop 0
	v_addc_co_u32_e32 v31, vcc, 0, v161, vcc
	global_store_dwordx4 v[30:31], v[24:27], off
	v_pk_mul_f32 v[16:17], v[136:137], v[16:17] op_sel_hi:[0,1]
	s_mov_b64 s[46:47], -1
	v_pk_mul_f32 v[24:25], v[138:139], v[14:15] op_sel_hi:[0,1]
	v_pk_mul_f32 v[14:15], v[138:139], v[12:13] op_sel_hi:[0,1]
	v_cvt_pk_bf16_f32 v12, v20, v21
	v_cvt_pk_bf16_f32 v13, v22, v23
	v_cvt_pk_bf16_f32 v14, v14, v15
	v_cvt_pk_bf16_f32 v15, v24, v25
	global_store_dwordx4 v[28:29], v[12:15], off offset:256
	v_pk_mul_f32 v[6:7], v[136:137], v[6:7] op_sel_hi:[0,1]
	v_pk_mul_f32 v[4:5], v[136:137], v[4:5] op_sel_hi:[0,1]
	v_pk_mul_f32 v[14:15], v[136:137], v[18:19] op_sel_hi:[0,1]
	v_pk_mul_f32 v[18:19], v[136:137], v[10:11] op_sel_hi:[0,1]
	v_pk_mul_f32 v[10:11], v[136:137], v[8:9] op_sel_hi:[0,1]
	v_cvt_pk_bf16_f32 v8, v16, v17
	v_cvt_pk_bf16_f32 v9, v14, v15
	v_add_co_u32_e32 v14, vcc, s86, v160
	v_lshl_add_u64 v[12:13], v[160:161], 0, s[38:39]
	s_nop 0
	v_addc_co_u32_e32 v15, vcc, 0, v161, vcc
	v_cvt_pk_bf16_f32 v10, v10, v11
	v_cvt_pk_bf16_f32 v11, v18, v19
	global_store_dwordx4 v[14:15], v[8:11], off
	s_and_b64 vcc, s[8:9], exec
	s_nop 0
	v_pk_mul_f32 v[8:9], v[136:137], v[2:3] op_sel_hi:[0,1]
	v_pk_mul_f32 v[2:3], v[136:137], v[0:1] op_sel_hi:[0,1]
	v_cvt_pk_bf16_f32 v0, v4, v5
	v_cvt_pk_bf16_f32 v1, v6, v7
	v_cvt_pk_bf16_f32 v2, v2, v3
	v_cvt_pk_bf16_f32 v3, v8, v9
	global_store_dwordx4 v[12:13], v[0:3], off offset:256
	s_cbranch_vccz .LBB0_315
	s_nop 0
	v_lshl_add_u32 v0, s87, 8, v137
	v_ashrrev_i32_e32 v1, 31, v0
	v_lshl_add_u64 v[0:1], v[0:1], 2, s[34:35]
	global_load_dword v158, v[0:1], off
	global_load_dword v156, v[0:1], off offset:64
	global_load_dword v154, v[0:1], off offset:128
	global_load_dword v152, v[0:1], off offset:192
	global_load_dword v150, v[0:1], off offset:512
	global_load_dword v140, v[0:1], off offset:576
	global_load_dword v138, v[0:1], off offset:640
	global_load_dword v136, v[0:1], off offset:704
	s_mov_b64 s[46:47], 0
	s_branch .LBB0_315
